# v108 + ph_win: hand-written epilogue for rope tiles on a row-scale cache hit (keeps the cache valid across the rope tile)
# speedup vs baseline: 1.0104x; 1.0004x over previous
;     DI void operator()(const f32x4 (&acc)[2][2][4][2], const Unit& u, int wr, int wc, int fr, int fq) const {
;         const int col0 = u.pn * BM + wc * 32 + 8 * fq;
;         const bool rope = u.pn < 4; const float ksc = (u.pn >= 2) ? 0.08838834764831845f : 1.0f;
;         const int fi = 4 * (4 * wc + fq);
;         const int rowb = u.pm * BM + wr * 64 + fr;
;         f32x4 sl[2][4];
; #pragma unroll
;         for (int ai = 0; ai < 2; ++ai)
; #pragma unroll
;             for (int m = 0; m < 4; ++m) sl[ai][m] = *(const f32x4*)(slots + (size_t)(rowb + ai * HALF + m * 16) * 16 + 4 * fq);
;         asm volatile("" ::: "memory");
; #pragma unroll
;         for (int ai = 0; ai < 2; ++ai) {
;             f32x4 c4[4], s4[4];
; #pragma unroll
;             for (int m = 0; m < 4; ++m) { c4[m] = (f32x4){1.f, 1.f, 1.f, 1.f}; s4[m] = (f32x4){0.f, 0.f, 0.f, 0.f}; }
;             if (rope) {
; #pragma unroll
;                 for (int m = 0; m < 4; ++m) { const int pos = (rowb + ai * HALF + m * 16) & (SEQ - 1); c4[m] = *(const f32x4*)(cs + pos * 64 + fi); s4[m] = *(const f32x4*)(sn + pos * 64 + fi); }
.LBB0_95:
	s_cmp_gt_i32 s60, 3
	s_cbranch_scc1 .Lwin_fast
	v_readlane_b32 s101, v255, 24
	s_nop 0
	s_cmp_eq_u32 s101, s6
	s_cbranch_scc1 .Lwin_rope_fast
	s_mov_b32 s101, -1
	v_writelane_b32 v255, s101, 24
	v_lshl_add_u32 v238, s6, 8, v1
	v_or_b32_e32 v236, 16, v238
	v_ashrrev_i32_e32 v239, 31, v238
	v_ashrrev_i32_e32 v237, 31, v236
	v_lshlrev_b64 v[66:67], 6, v[238:239]
	v_lshlrev_b64 v[68:69], 6, v[236:237]
	v_or_b32_e32 v234, 32, v238
	v_or_b32_e32 v232, 48, v238
	v_lshl_add_u64 v[66:67], v[214:215], 0, v[66:67]
	v_lshl_add_u64 v[68:69], v[214:215], 0, v[68:69]
	v_ashrrev_i32_e32 v235, 31, v234
	v_ashrrev_i32_e32 v233, 31, v232
	global_load_dwordx4 v[190:193], v[66:67], off
	global_load_dwordx4 v[178:181], v[68:69], off
	v_lshlrev_b64 v[66:67], 6, v[234:235]
	v_lshlrev_b64 v[68:69], 6, v[232:233]
	v_add_u32_e32 v230, 0x80, v238
	v_add_u32_e32 v228, 0x90, v238
	v_lshl_add_u64 v[66:67], v[214:215], 0, v[66:67]
	v_lshl_add_u64 v[68:69], v[214:215], 0, v[68:69]
	v_ashrrev_i32_e32 v231, 31, v230
	v_ashrrev_i32_e32 v229, 31, v228
	global_load_dwordx4 v[166:169], v[66:67], off
	global_load_dwordx4 v[154:157], v[68:69], off
	v_lshlrev_b64 v[66:67], 6, v[230:231]
	v_lshlrev_b64 v[68:69], 6, v[228:229]
	v_add_u32_e32 v226, 0xa0, v238
	v_add_u32_e32 v224, 0xb0, v238
	v_lshl_add_u64 v[66:67], v[214:215], 0, v[66:67]
	v_lshl_add_u64 v[68:69], v[214:215], 0, v[68:69]
	v_ashrrev_i32_e32 v227, 31, v226
	v_ashrrev_i32_e32 v225, 31, v224
	global_load_dwordx4 v[118:121], v[66:67], off
	global_load_dwordx4 v[98:101], v[68:69], off
	v_lshlrev_b64 v[66:67], 6, v[226:227]
	v_lshlrev_b64 v[68:69], 6, v[224:225]
	v_lshl_add_u64 v[66:67], v[214:215], 0, v[66:67]
	v_lshl_add_u64 v[68:69], v[214:215], 0, v[68:69]
	global_load_dwordx4 v[78:81], v[66:67], off
	s_nop 0
	global_load_dwordx4 v[66:69], v[68:69], off
	s_cmp_lt_i32 s60, 4
	s_cselect_b64 s[62:63], -1, 0
	s_cmp_gt_i32 s60, 3
	v_lshlrev_b32_e32 v229, 6, v238
	s_cbranch_scc1 .LBB0_97
	v_lshlrev_b32_e32 v138, 2, v229
	v_and_b32_e32 v138, 0xfcf00, v138
	v_mov_b32_e32 v139, v0
	v_lshl_add_u64 v[140:141], v[216:217], 0, v[138:139]
	v_lshl_add_u64 v[142:143], v[218:219], 0, v[138:139]
	global_load_dwordx4 v[186:189], v[140:141], off
	global_load_dwordx4 v[182:185], v[142:143], off
	v_or_b32_e32 v140, 0x1000, v138
	v_mov_b32_e32 v141, v0
	v_lshl_add_u64 v[142:143], v[216:217], 0, v[140:141]
	v_lshl_add_u64 v[140:141], v[218:219], 0, v[140:141]
	global_load_dwordx4 v[174:177], v[142:143], off
	global_load_dwordx4 v[170:173], v[140:141], off
	v_or_b32_e32 v140, 0x2000, v138
	v_mov_b32_e32 v141, v0
	v_lshl_add_u64 v[142:143], v[216:217], 0, v[140:141]
	v_lshl_add_u64 v[140:141], v[218:219], 0, v[140:141]
	v_or_b32_e32 v138, 0x3000, v138
	global_load_dwordx4 v[162:165], v[142:143], off
	global_load_dwordx4 v[158:161], v[140:141], off
	v_lshl_add_u64 v[140:141], v[216:217], 0, v[138:139]
	v_lshl_add_u64 v[138:139], v[218:219], 0, v[138:139]
	global_load_dwordx4 v[142:145], v[140:141], off
	s_nop 0
	global_load_dwordx4 v[138:141], v[138:139], off
	s_branch .LBB0_98

; DI unsigned pk2(float lo, float hi) { unsigned r; asm("v_cvt_pk_bf16_f32 %0, %1, %2" : "=v"(r) : "v"(lo), "v"(hi)); return r; }
;     DI void operator()(const f32x4 (&acc)[2][2][4][2], const Unit& u, int wr, int wc, int fr, int fq) const {
;     ...
;             if (rope) {
; #pragma unroll
;                 for (int m = 0; m < 4; ++m) { const int pos = (rowb + ai * HALF + m * 16) & (SEQ - 1); c4[m] = *(const f32x4*)(cs + pos * 64 + fi); s4[m] = *(const f32x4*)(sn + pos * 64 + fi); }
;             }
;             asm volatile("" ::: "memory");
; #pragma unroll
;             for (int m = 0; m < 4; ++m) {
;                 const int row = rowb + ai * HALF + m * 16;
;                 float t = (sl[ai][m][0] + sl[ai][m][1]) + (sl[ai][m][2] + sl[ai][m][3]);
;                 t += __shfl_xor(t, 16); t += __shfl_xor(t, 32);
;                 const float rs = __builtin_amdgcn_rsqf(t * (1.0f / D) + EPS);
; #pragma unroll
;                 for (int bj = 0; bj < 2; ++bj) {
;                     f32x4 v0 = acc[ai][bj][m][0] * rs, v1 = acc[ai][bj][m][1] * rs;
;                     if (rope) { const f32x4 o0 = (v0 * c4[m] - v1 * s4[m]) * ksc, o1 = (v0 * s4[m] + v1 * c4[m]) * ksc; v0 = o0; v1 = o1; }
;                     u32x4 w; w.x = pk2(v0[0], v0[1]); w.y = pk2(v0[2], v0[3]); w.z = pk2(v1[0], v1[1]); w.w = pk2(v1[2], v1[3]);
;                     *(u32x4*)(Z + (size_t)row * INW + col0 + bj * HALF) = w;
;                 }
.Lwin_rope_fast:
	v_lshl_add_u32 v234, s6, 8, v1
	v_mov_b32_e32 v229, 0
	v_lshlrev_b32_e32 v161, 8, v234
	v_and_b32_e32 v161, 0xfff00, v161
	v_mov_b32_e32 v228, v161
	v_lshl_add_u64 v[226:227], v[216:217], 0, v[228:229]
	v_lshl_add_u64 v[154:155], v[218:219], 0, v[228:229]
	global_load_dwordx4 v[162:165], v[226:227], off
	global_load_dwordx4 v[166:169], v[154:155], off
	v_add_u32_e32 v228, 0x1000, v161
	v_lshl_add_u64 v[226:227], v[216:217], 0, v[228:229]
	v_lshl_add_u64 v[154:155], v[218:219], 0, v[228:229]
	global_load_dwordx4 v[170:173], v[226:227], off
	global_load_dwordx4 v[174:177], v[154:155], off
	v_add_u32_e32 v228, 0x2000, v161
	v_lshl_add_u64 v[226:227], v[216:217], 0, v[228:229]
	v_lshl_add_u64 v[154:155], v[218:219], 0, v[228:229]
	global_load_dwordx4 v[178:181], v[226:227], off
	global_load_dwordx4 v[182:185], v[154:155], off
	v_add_u32_e32 v228, 0x3000, v161
	v_lshl_add_u64 v[226:227], v[216:217], 0, v[228:229]
	v_lshl_add_u64 v[154:155], v[218:219], 0, v[228:229]
	global_load_dwordx4 v[186:189], v[226:227], off
	global_load_dwordx4 v[190:193], v[154:155], off
	v_lshl_or_b32 v160, s60, 8, v254
	v_mul_lo_u32 v138, v234, s78
	s_cmp_gt_i32 s60, 1
	v_lshl_add_u32 v138, v160, 1, v138
	s_cselect_b32 s101, 0x3db504f3, 1.0
	v_add_u32_e32 v139, 0x4c000, v138
	v_add_u32_e32 v140, 0x98000, v138
	v_add_u32_e32 v141, 0xe4000, v138
	v_add_u32_e32 v142, 0x260000, v138
	v_add_u32_e32 v143, 0x2ac000, v138
	v_add_u32_e32 v144, 0x2f8000, v138
	v_add_u32_e32 v145, 0x344000, v138
	v_mov_b32_e32 v224, s101
	s_waitcnt vmcnt(6)
	v_pk_mul_f32 v[150:151], v[150:151], v[204:205] op_sel_hi:[1,0]
	v_pk_mul_f32 v[152:153], v[152:153], v[204:205] op_sel_hi:[1,0]
	v_pk_mul_f32 v[146:147], v[146:147], v[204:205] op_sel_hi:[1,0]
	v_pk_mul_f32 v[148:149], v[148:149], v[204:205] op_sel_hi:[1,0]
	v_pk_mul_f32 v[200:201], v[166:167], v[146:147]
	v_pk_mul_f32 v[236:237], v[162:163], v[146:147]
	v_pk_mul_f32 v[202:203], v[168:169], v[148:149]
	v_pk_mul_f32 v[238:239], v[164:165], v[148:149]
	v_pk_fma_f32 v[146:147], v[166:167], v[150:151], v[236:237]
	v_pk_fma_f32 v[150:151], v[162:163], v[150:151], v[200:201] neg_lo:[0,0,1] neg_hi:[0,0,1]
	v_pk_fma_f32 v[148:149], v[168:169], v[152:153], v[238:239]
	v_pk_fma_f32 v[152:153], v[164:165], v[152:153], v[202:203] neg_lo:[0,0,1] neg_hi:[0,0,1]
	v_pk_mul_f32 v[150:151], v[150:151], v[224:225] op_sel_hi:[1,0]
	v_pk_mul_f32 v[152:153], v[152:153], v[224:225] op_sel_hi:[1,0]
	v_pk_mul_f32 v[146:147], v[146:147], v[224:225] op_sel_hi:[1,0]
	v_pk_mul_f32 v[148:149], v[148:149], v[224:225] op_sel_hi:[1,0]
	v_cvt_pk_bf16_f32 v66, v150, v151
	v_cvt_pk_bf16_f32 v67, v152, v153
	v_cvt_pk_bf16_f32 v68, v146, v147
	v_cvt_pk_bf16_f32 v69, v148, v149
	v_pk_mul_f32 v[134:135], v[134:135], v[204:205] op_sel_hi:[1,0]
	v_pk_mul_f32 v[136:137], v[136:137], v[204:205] op_sel_hi:[1,0]
	v_pk_mul_f32 v[130:131], v[130:131], v[204:205] op_sel_hi:[1,0]
	v_pk_mul_f32 v[132:133], v[132:133], v[204:205] op_sel_hi:[1,0]
	v_pk_mul_f32 v[200:201], v[166:167], v[130:131]
	v_pk_mul_f32 v[236:237], v[162:163], v[130:131]
	v_pk_mul_f32 v[202:203], v[168:169], v[132:133]
	v_pk_mul_f32 v[238:239], v[164:165], v[132:133]
	v_pk_fma_f32 v[130:131], v[166:167], v[134:135], v[236:237]
	v_pk_fma_f32 v[134:135], v[162:163], v[134:135], v[200:201] neg_lo:[0,0,1] neg_hi:[0,0,1]
	v_pk_fma_f32 v[132:133], v[168:169], v[136:137], v[238:239]
	v_pk_fma_f32 v[136:137], v[164:165], v[136:137], v[202:203] neg_lo:[0,0,1] neg_hi:[0,0,1]
	v_pk_mul_f32 v[134:135], v[134:135], v[224:225] op_sel_hi:[1,0]
	v_pk_mul_f32 v[136:137], v[136:137], v[224:225] op_sel_hi:[1,0]
	v_pk_mul_f32 v[130:131], v[130:131], v[224:225] op_sel_hi:[1,0]
	v_pk_mul_f32 v[132:133], v[132:133], v[224:225] op_sel_hi:[1,0]
	v_cvt_pk_bf16_f32 v78, v134, v135
	v_cvt_pk_bf16_f32 v79, v136, v137
	v_cvt_pk_bf16_f32 v80, v130, v131
	v_cvt_pk_bf16_f32 v81, v132, v133
	v_add_u32_e32 v228, 0x8000, v161
	v_lshl_add_u64 v[226:227], v[216:217], 0, v[228:229]
	v_lshl_add_u64 v[154:155], v[218:219], 0, v[228:229]
	global_load_dwordx4 v[162:165], v[226:227], off
	global_load_dwordx4 v[166:169], v[154:155], off
	global_store_dwordx4 v138, v[66:69], s[48:49]
	global_store_dwordx4 v138, v[78:81], s[48:49] offset:256
	s_waitcnt vmcnt(8)
	v_pk_mul_f32 v[126:127], v[126:127], v[204:205] op_sel:[0,1] op_sel_hi:[1,1]
	v_pk_mul_f32 v[128:129], v[128:129], v[204:205] op_sel:[0,1] op_sel_hi:[1,1]
	v_pk_mul_f32 v[122:123], v[122:123], v[204:205] op_sel:[0,1] op_sel_hi:[1,1]
	v_pk_mul_f32 v[124:125], v[124:125], v[204:205] op_sel:[0,1] op_sel_hi:[1,1]
	v_pk_mul_f32 v[200:201], v[174:175], v[122:123]
	v_pk_mul_f32 v[236:237], v[170:171], v[122:123]
	v_pk_mul_f32 v[202:203], v[176:177], v[124:125]
	v_pk_mul_f32 v[238:239], v[172:173], v[124:125]
	v_pk_fma_f32 v[122:123], v[174:175], v[126:127], v[236:237]
	v_pk_fma_f32 v[126:127], v[170:171], v[126:127], v[200:201] neg_lo:[0,0,1] neg_hi:[0,0,1]
	v_pk_fma_f32 v[124:125], v[176:177], v[128:129], v[238:239]
	v_pk_fma_f32 v[128:129], v[172:173], v[128:129], v[202:203] neg_lo:[0,0,1] neg_hi:[0,0,1]
	v_pk_mul_f32 v[126:127], v[126:127], v[224:225] op_sel_hi:[1,0]
	v_pk_mul_f32 v[128:129], v[128:129], v[224:225] op_sel_hi:[1,0]
	v_pk_mul_f32 v[122:123], v[122:123], v[224:225] op_sel_hi:[1,0]
	v_pk_mul_f32 v[124:125], v[124:125], v[224:225] op_sel_hi:[1,0]
	v_cvt_pk_bf16_f32 v66, v126, v127
	v_cvt_pk_bf16_f32 v67, v128, v129
	v_cvt_pk_bf16_f32 v68, v122, v123
	v_cvt_pk_bf16_f32 v69, v124, v125
	v_pk_mul_f32 v[114:115], v[114:115], v[204:205] op_sel:[0,1] op_sel_hi:[1,1]
	v_pk_mul_f32 v[116:117], v[116:117], v[204:205] op_sel:[0,1] op_sel_hi:[1,1]
	v_pk_mul_f32 v[110:111], v[110:111], v[204:205] op_sel:[0,1] op_sel_hi:[1,1]
	v_pk_mul_f32 v[112:113], v[112:113], v[204:205] op_sel:[0,1] op_sel_hi:[1,1]
	v_pk_mul_f32 v[200:201], v[174:175], v[110:111]
	v_pk_mul_f32 v[236:237], v[170:171], v[110:111]
	v_pk_mul_f32 v[202:203], v[176:177], v[112:113]
	v_pk_mul_f32 v[238:239], v[172:173], v[112:113]
	v_pk_fma_f32 v[110:111], v[174:175], v[114:115], v[236:237]
	v_pk_fma_f32 v[114:115], v[170:171], v[114:115], v[200:201] neg_lo:[0,0,1] neg_hi:[0,0,1]
	v_pk_fma_f32 v[112:113], v[176:177], v[116:117], v[238:239]
	v_pk_fma_f32 v[116:117], v[172:173], v[116:117], v[202:203] neg_lo:[0,0,1] neg_hi:[0,0,1]
	v_pk_mul_f32 v[114:115], v[114:115], v[224:225] op_sel_hi:[1,0]
	v_pk_mul_f32 v[116:117], v[116:117], v[224:225] op_sel_hi:[1,0]
	v_pk_mul_f32 v[110:111], v[110:111], v[224:225] op_sel_hi:[1,0]
	v_pk_mul_f32 v[112:113], v[112:113], v[224:225] op_sel_hi:[1,0]
	v_cvt_pk_bf16_f32 v78, v114, v115
	v_cvt_pk_bf16_f32 v79, v116, v117
	v_cvt_pk_bf16_f32 v80, v110, v111
	v_cvt_pk_bf16_f32 v81, v112, v113
	v_add_u32_e32 v228, 0x9000, v161
	v_lshl_add_u64 v[226:227], v[216:217], 0, v[228:229]
	v_lshl_add_u64 v[154:155], v[218:219], 0, v[228:229]
	global_load_dwordx4 v[170:173], v[226:227], off
	global_load_dwordx4 v[174:177], v[154:155], off
	global_store_dwordx4 v139, v[66:69], s[48:49]
	global_store_dwordx4 v139, v[78:81], s[48:49] offset:256
	s_waitcnt vmcnt(10)
; DI unsigned pk2(float lo, float hi) { unsigned r; asm("v_cvt_pk_bf16_f32 %0, %1, %2" : "=v"(r) : "v"(lo), "v"(hi)); return r; }
;     DI void operator()(const f32x4 (&acc)[2][2][4][2], const Unit& u, int wr, int wc, int fr, int fq) const {
;     ...
;             if (rope) {
; #pragma unroll
;                 for (int m = 0; m < 4; ++m) { const int pos = (rowb + ai * HALF + m * 16) & (SEQ - 1); c4[m] = *(const f32x4*)(cs + pos * 64 + fi); s4[m] = *(const f32x4*)(sn + pos * 64 + fi); }
;             }
;             asm volatile("" ::: "memory");
; #pragma unroll
;             for (int m = 0; m < 4; ++m) {
;                 const int row = rowb + ai * HALF + m * 16;
;                 float t = (sl[ai][m][0] + sl[ai][m][1]) + (sl[ai][m][2] + sl[ai][m][3]);
;                 t += __shfl_xor(t, 16); t += __shfl_xor(t, 32);
;                 const float rs = __builtin_amdgcn_rsqf(t * (1.0f / D) + EPS);
; #pragma unroll
;                 for (int bj = 0; bj < 2; ++bj) {
;                     f32x4 v0 = acc[ai][bj][m][0] * rs, v1 = acc[ai][bj][m][1] * rs;
;                     if (rope) { const f32x4 o0 = (v0 * c4[m] - v1 * s4[m]) * ksc, o1 = (v0 * s4[m] + v1 * c4[m]) * ksc; v0 = o0; v1 = o1; }
;                     u32x4 w; w.x = pk2(v0[0], v0[1]); w.y = pk2(v0[2], v0[3]); w.z = pk2(v1[0], v1[1]); w.w = pk2(v1[2], v1[3]);
;                     *(u32x4*)(Z + (size_t)row * INW + col0 + bj * HALF) = w;
;                 }
	v_pk_mul_f32 v[106:107], v[106:107], v[230:231] op_sel_hi:[1,0]
	v_pk_mul_f32 v[108:109], v[108:109], v[230:231] op_sel_hi:[1,0]
	v_pk_mul_f32 v[102:103], v[102:103], v[230:231] op_sel_hi:[1,0]
	v_pk_mul_f32 v[104:105], v[104:105], v[230:231] op_sel_hi:[1,0]
	v_pk_mul_f32 v[200:201], v[182:183], v[102:103]
	v_pk_mul_f32 v[236:237], v[178:179], v[102:103]
	v_pk_mul_f32 v[202:203], v[184:185], v[104:105]
	v_pk_mul_f32 v[238:239], v[180:181], v[104:105]
	v_pk_fma_f32 v[102:103], v[182:183], v[106:107], v[236:237]
	v_pk_fma_f32 v[106:107], v[178:179], v[106:107], v[200:201] neg_lo:[0,0,1] neg_hi:[0,0,1]
	v_pk_fma_f32 v[104:105], v[184:185], v[108:109], v[238:239]
	v_pk_fma_f32 v[108:109], v[180:181], v[108:109], v[202:203] neg_lo:[0,0,1] neg_hi:[0,0,1]
	v_pk_mul_f32 v[106:107], v[106:107], v[224:225] op_sel_hi:[1,0]
	v_pk_mul_f32 v[108:109], v[108:109], v[224:225] op_sel_hi:[1,0]
	v_pk_mul_f32 v[102:103], v[102:103], v[224:225] op_sel_hi:[1,0]
	v_pk_mul_f32 v[104:105], v[104:105], v[224:225] op_sel_hi:[1,0]
	v_cvt_pk_bf16_f32 v66, v106, v107
	v_cvt_pk_bf16_f32 v67, v108, v109
	v_cvt_pk_bf16_f32 v68, v102, v103
	v_cvt_pk_bf16_f32 v69, v104, v105
	v_pk_mul_f32 v[94:95], v[94:95], v[230:231] op_sel_hi:[1,0]
	v_pk_mul_f32 v[96:97], v[96:97], v[230:231] op_sel_hi:[1,0]
	v_pk_mul_f32 v[90:91], v[90:91], v[230:231] op_sel_hi:[1,0]
	v_pk_mul_f32 v[92:93], v[92:93], v[230:231] op_sel_hi:[1,0]
	v_pk_mul_f32 v[200:201], v[182:183], v[90:91]
	v_pk_mul_f32 v[236:237], v[178:179], v[90:91]
	v_pk_mul_f32 v[202:203], v[184:185], v[92:93]
	v_pk_mul_f32 v[238:239], v[180:181], v[92:93]
	v_pk_fma_f32 v[90:91], v[182:183], v[94:95], v[236:237]
	v_pk_fma_f32 v[94:95], v[178:179], v[94:95], v[200:201] neg_lo:[0,0,1] neg_hi:[0,0,1]
	v_pk_fma_f32 v[92:93], v[184:185], v[96:97], v[238:239]
	v_pk_fma_f32 v[96:97], v[180:181], v[96:97], v[202:203] neg_lo:[0,0,1] neg_hi:[0,0,1]
	v_pk_mul_f32 v[94:95], v[94:95], v[224:225] op_sel_hi:[1,0]
	v_pk_mul_f32 v[96:97], v[96:97], v[224:225] op_sel_hi:[1,0]
	v_pk_mul_f32 v[90:91], v[90:91], v[224:225] op_sel_hi:[1,0]
	v_pk_mul_f32 v[92:93], v[92:93], v[224:225] op_sel_hi:[1,0]
	v_cvt_pk_bf16_f32 v78, v94, v95
	v_cvt_pk_bf16_f32 v79, v96, v97
	v_cvt_pk_bf16_f32 v80, v90, v91
	v_cvt_pk_bf16_f32 v81, v92, v93
	v_add_u32_e32 v228, 0xa000, v161
	v_lshl_add_u64 v[226:227], v[216:217], 0, v[228:229]
	v_lshl_add_u64 v[154:155], v[218:219], 0, v[228:229]
	global_load_dwordx4 v[178:181], v[226:227], off
	global_load_dwordx4 v[182:185], v[154:155], off
	global_store_dwordx4 v140, v[66:69], s[48:49]
	global_store_dwordx4 v140, v[78:81], s[48:49] offset:256
	s_waitcnt vmcnt(12)
	v_pk_mul_f32 v[86:87], v[86:87], v[230:231] op_sel:[0,1] op_sel_hi:[1,1]
	v_pk_mul_f32 v[88:89], v[88:89], v[230:231] op_sel:[0,1] op_sel_hi:[1,1]
	v_pk_mul_f32 v[82:83], v[82:83], v[230:231] op_sel:[0,1] op_sel_hi:[1,1]
	v_pk_mul_f32 v[84:85], v[84:85], v[230:231] op_sel:[0,1] op_sel_hi:[1,1]
	v_pk_mul_f32 v[200:201], v[190:191], v[82:83]
	v_pk_mul_f32 v[236:237], v[186:187], v[82:83]
	v_pk_mul_f32 v[202:203], v[192:193], v[84:85]
	v_pk_mul_f32 v[238:239], v[188:189], v[84:85]
	v_pk_fma_f32 v[82:83], v[190:191], v[86:87], v[236:237]
	v_pk_fma_f32 v[86:87], v[186:187], v[86:87], v[200:201] neg_lo:[0,0,1] neg_hi:[0,0,1]
	v_pk_fma_f32 v[84:85], v[192:193], v[88:89], v[238:239]
	v_pk_fma_f32 v[88:89], v[188:189], v[88:89], v[202:203] neg_lo:[0,0,1] neg_hi:[0,0,1]
	v_pk_mul_f32 v[86:87], v[86:87], v[224:225] op_sel_hi:[1,0]
	v_pk_mul_f32 v[88:89], v[88:89], v[224:225] op_sel_hi:[1,0]
	v_pk_mul_f32 v[82:83], v[82:83], v[224:225] op_sel_hi:[1,0]
	v_pk_mul_f32 v[84:85], v[84:85], v[224:225] op_sel_hi:[1,0]
	v_cvt_pk_bf16_f32 v66, v86, v87
	v_cvt_pk_bf16_f32 v67, v88, v89
	v_cvt_pk_bf16_f32 v68, v82, v83
	v_cvt_pk_bf16_f32 v69, v84, v85
	v_pk_mul_f32 v[74:75], v[74:75], v[230:231] op_sel:[0,1] op_sel_hi:[1,1]
	v_pk_mul_f32 v[76:77], v[76:77], v[230:231] op_sel:[0,1] op_sel_hi:[1,1]
	v_pk_mul_f32 v[70:71], v[70:71], v[230:231] op_sel:[0,1] op_sel_hi:[1,1]
	v_pk_mul_f32 v[72:73], v[72:73], v[230:231] op_sel:[0,1] op_sel_hi:[1,1]
	v_pk_mul_f32 v[200:201], v[190:191], v[70:71]
	v_pk_mul_f32 v[236:237], v[186:187], v[70:71]
	v_pk_mul_f32 v[202:203], v[192:193], v[72:73]
	v_pk_mul_f32 v[238:239], v[188:189], v[72:73]
	v_pk_fma_f32 v[70:71], v[190:191], v[74:75], v[236:237]
	v_pk_fma_f32 v[74:75], v[186:187], v[74:75], v[200:201] neg_lo:[0,0,1] neg_hi:[0,0,1]
	v_pk_fma_f32 v[72:73], v[192:193], v[76:77], v[238:239]
	v_pk_fma_f32 v[76:77], v[188:189], v[76:77], v[202:203] neg_lo:[0,0,1] neg_hi:[0,0,1]
	v_pk_mul_f32 v[74:75], v[74:75], v[224:225] op_sel_hi:[1,0]
	v_pk_mul_f32 v[76:77], v[76:77], v[224:225] op_sel_hi:[1,0]
	v_pk_mul_f32 v[70:71], v[70:71], v[224:225] op_sel_hi:[1,0]
	v_pk_mul_f32 v[72:73], v[72:73], v[224:225] op_sel_hi:[1,0]
	v_cvt_pk_bf16_f32 v78, v74, v75
	v_cvt_pk_bf16_f32 v79, v76, v77
	v_cvt_pk_bf16_f32 v80, v70, v71
	v_cvt_pk_bf16_f32 v81, v72, v73
	v_add_u32_e32 v228, 0xb000, v161
	v_lshl_add_u64 v[226:227], v[216:217], 0, v[228:229]
	v_lshl_add_u64 v[154:155], v[218:219], 0, v[228:229]
	global_load_dwordx4 v[186:189], v[226:227], off
	global_load_dwordx4 v[190:193], v[154:155], off
	global_store_dwordx4 v141, v[66:69], s[48:49]
	global_store_dwordx4 v141, v[78:81], s[48:49] offset:256
	s_waitcnt vmcnt(14)
; DI unsigned pk2(float lo, float hi) { unsigned r; asm("v_cvt_pk_bf16_f32 %0, %1, %2" : "=v"(r) : "v"(lo), "v"(hi)); return r; }
;     DI void operator()(const f32x4 (&acc)[2][2][4][2], const Unit& u, int wr, int wc, int fr, int fq) const {
;     ...
;             if (rope) {
; #pragma unroll
;                 for (int m = 0; m < 4; ++m) { const int pos = (rowb + ai * HALF + m * 16) & (SEQ - 1); c4[m] = *(const f32x4*)(cs + pos * 64 + fi); s4[m] = *(const f32x4*)(sn + pos * 64 + fi); }
;             }
;             asm volatile("" ::: "memory");
; #pragma unroll
;             for (int m = 0; m < 4; ++m) {
;                 const int row = rowb + ai * HALF + m * 16;
;                 float t = (sl[ai][m][0] + sl[ai][m][1]) + (sl[ai][m][2] + sl[ai][m][3]);
;                 t += __shfl_xor(t, 16); t += __shfl_xor(t, 32);
;                 const float rs = __builtin_amdgcn_rsqf(t * (1.0f / D) + EPS);
; #pragma unroll
;                 for (int bj = 0; bj < 2; ++bj) {
;                     f32x4 v0 = acc[ai][bj][m][0] * rs, v1 = acc[ai][bj][m][1] * rs;
;                     if (rope) { const f32x4 o0 = (v0 * c4[m] - v1 * s4[m]) * ksc, o1 = (v0 * s4[m] + v1 * c4[m]) * ksc; v0 = o0; v1 = o1; }
;                     u32x4 w; w.x = pk2(v0[0], v0[1]); w.y = pk2(v0[2], v0[3]); w.z = pk2(v1[0], v1[1]); w.w = pk2(v1[2], v1[3]);
;                     *(u32x4*)(Z + (size_t)row * INW + col0 + bj * HALF) = w;
;                 }
	v_pk_mul_f32 v[62:63], v[62:63], v[232:233] op_sel:[0,1] op_sel_hi:[1,1]
	v_pk_mul_f32 v[64:65], v[64:65], v[232:233] op_sel:[0,1] op_sel_hi:[1,1]
	v_pk_mul_f32 v[58:59], v[58:59], v[232:233] op_sel:[0,1] op_sel_hi:[1,1]
	v_pk_mul_f32 v[60:61], v[60:61], v[232:233] op_sel:[0,1] op_sel_hi:[1,1]
	v_pk_mul_f32 v[200:201], v[166:167], v[58:59]
	v_pk_mul_f32 v[236:237], v[162:163], v[58:59]
	v_pk_mul_f32 v[202:203], v[168:169], v[60:61]
	v_pk_mul_f32 v[238:239], v[164:165], v[60:61]
	v_pk_fma_f32 v[58:59], v[166:167], v[62:63], v[236:237]
	v_pk_fma_f32 v[62:63], v[162:163], v[62:63], v[200:201] neg_lo:[0,0,1] neg_hi:[0,0,1]
	v_pk_fma_f32 v[60:61], v[168:169], v[64:65], v[238:239]
	v_pk_fma_f32 v[64:65], v[164:165], v[64:65], v[202:203] neg_lo:[0,0,1] neg_hi:[0,0,1]
	v_pk_mul_f32 v[62:63], v[62:63], v[224:225] op_sel_hi:[1,0]
	v_pk_mul_f32 v[64:65], v[64:65], v[224:225] op_sel_hi:[1,0]
	v_pk_mul_f32 v[58:59], v[58:59], v[224:225] op_sel_hi:[1,0]
	v_pk_mul_f32 v[60:61], v[60:61], v[224:225] op_sel_hi:[1,0]
	v_cvt_pk_bf16_f32 v66, v62, v63
	v_cvt_pk_bf16_f32 v67, v64, v65
	v_cvt_pk_bf16_f32 v68, v58, v59
	v_cvt_pk_bf16_f32 v69, v60, v61
	v_pk_mul_f32 v[54:55], v[54:55], v[232:233] op_sel:[0,1] op_sel_hi:[1,1]
	v_pk_mul_f32 v[56:57], v[56:57], v[232:233] op_sel:[0,1] op_sel_hi:[1,1]
	v_pk_mul_f32 v[50:51], v[50:51], v[232:233] op_sel:[0,1] op_sel_hi:[1,1]
	v_pk_mul_f32 v[52:53], v[52:53], v[232:233] op_sel:[0,1] op_sel_hi:[1,1]
	v_pk_mul_f32 v[200:201], v[166:167], v[50:51]
	v_pk_mul_f32 v[236:237], v[162:163], v[50:51]
	v_pk_mul_f32 v[202:203], v[168:169], v[52:53]
	v_pk_mul_f32 v[238:239], v[164:165], v[52:53]
	v_pk_fma_f32 v[50:51], v[166:167], v[54:55], v[236:237]
	v_pk_fma_f32 v[54:55], v[162:163], v[54:55], v[200:201] neg_lo:[0,0,1] neg_hi:[0,0,1]
	v_pk_fma_f32 v[52:53], v[168:169], v[56:57], v[238:239]
	v_pk_fma_f32 v[56:57], v[164:165], v[56:57], v[202:203] neg_lo:[0,0,1] neg_hi:[0,0,1]
	v_pk_mul_f32 v[54:55], v[54:55], v[224:225] op_sel_hi:[1,0]
	v_pk_mul_f32 v[56:57], v[56:57], v[224:225] op_sel_hi:[1,0]
	v_pk_mul_f32 v[50:51], v[50:51], v[224:225] op_sel_hi:[1,0]
	v_pk_mul_f32 v[52:53], v[52:53], v[224:225] op_sel_hi:[1,0]
	v_cvt_pk_bf16_f32 v78, v54, v55
	v_cvt_pk_bf16_f32 v79, v56, v57
	v_cvt_pk_bf16_f32 v80, v50, v51
	v_cvt_pk_bf16_f32 v81, v52, v53
	global_store_dwordx4 v142, v[66:69], s[48:49]
	global_store_dwordx4 v142, v[78:81], s[48:49] offset:256
	s_waitcnt vmcnt(12)
	v_pk_mul_f32 v[46:47], v[46:47], v[234:235] op_sel:[0,1] op_sel_hi:[1,1]
	v_pk_mul_f32 v[48:49], v[48:49], v[234:235] op_sel:[0,1] op_sel_hi:[1,1]
	v_pk_mul_f32 v[42:43], v[42:43], v[234:235] op_sel:[0,1] op_sel_hi:[1,1]
	v_pk_mul_f32 v[44:45], v[44:45], v[234:235] op_sel:[0,1] op_sel_hi:[1,1]
	v_pk_mul_f32 v[200:201], v[174:175], v[42:43]
	v_pk_mul_f32 v[236:237], v[170:171], v[42:43]
	v_pk_mul_f32 v[202:203], v[176:177], v[44:45]
	v_pk_mul_f32 v[238:239], v[172:173], v[44:45]
	v_pk_fma_f32 v[42:43], v[174:175], v[46:47], v[236:237]
	v_pk_fma_f32 v[46:47], v[170:171], v[46:47], v[200:201] neg_lo:[0,0,1] neg_hi:[0,0,1]
	v_pk_fma_f32 v[44:45], v[176:177], v[48:49], v[238:239]
	v_pk_fma_f32 v[48:49], v[172:173], v[48:49], v[202:203] neg_lo:[0,0,1] neg_hi:[0,0,1]
	v_pk_mul_f32 v[46:47], v[46:47], v[224:225] op_sel_hi:[1,0]
	v_pk_mul_f32 v[48:49], v[48:49], v[224:225] op_sel_hi:[1,0]
	v_pk_mul_f32 v[42:43], v[42:43], v[224:225] op_sel_hi:[1,0]
	v_pk_mul_f32 v[44:45], v[44:45], v[224:225] op_sel_hi:[1,0]
	v_cvt_pk_bf16_f32 v66, v46, v47
	v_cvt_pk_bf16_f32 v67, v48, v49
	v_cvt_pk_bf16_f32 v68, v42, v43
	v_cvt_pk_bf16_f32 v69, v44, v45
	v_pk_mul_f32 v[38:39], v[38:39], v[234:235] op_sel:[0,1] op_sel_hi:[1,1]
	v_pk_mul_f32 v[40:41], v[40:41], v[234:235] op_sel:[0,1] op_sel_hi:[1,1]
	v_pk_mul_f32 v[34:35], v[34:35], v[234:235] op_sel:[0,1] op_sel_hi:[1,1]
	v_pk_mul_f32 v[36:37], v[36:37], v[234:235] op_sel:[0,1] op_sel_hi:[1,1]
	v_pk_mul_f32 v[200:201], v[174:175], v[34:35]
	v_pk_mul_f32 v[236:237], v[170:171], v[34:35]
	v_pk_mul_f32 v[202:203], v[176:177], v[36:37]
	v_pk_mul_f32 v[238:239], v[172:173], v[36:37]
	v_pk_fma_f32 v[34:35], v[174:175], v[38:39], v[236:237]
	v_pk_fma_f32 v[38:39], v[170:171], v[38:39], v[200:201] neg_lo:[0,0,1] neg_hi:[0,0,1]
	v_pk_fma_f32 v[36:37], v[176:177], v[40:41], v[238:239]
	v_pk_fma_f32 v[40:41], v[172:173], v[40:41], v[202:203] neg_lo:[0,0,1] neg_hi:[0,0,1]
	v_pk_mul_f32 v[38:39], v[38:39], v[224:225] op_sel_hi:[1,0]
	v_pk_mul_f32 v[40:41], v[40:41], v[224:225] op_sel_hi:[1,0]
	v_pk_mul_f32 v[34:35], v[34:35], v[224:225] op_sel_hi:[1,0]
	v_pk_mul_f32 v[36:37], v[36:37], v[224:225] op_sel_hi:[1,0]
	v_cvt_pk_bf16_f32 v78, v38, v39
	v_cvt_pk_bf16_f32 v79, v40, v41
	v_cvt_pk_bf16_f32 v80, v34, v35
	v_cvt_pk_bf16_f32 v81, v36, v37
	global_store_dwordx4 v143, v[66:69], s[48:49]
	global_store_dwordx4 v143, v[78:81], s[48:49] offset:256
	s_waitcnt vmcnt(10)
; DI unsigned pk2(float lo, float hi) { unsigned r; asm("v_cvt_pk_bf16_f32 %0, %1, %2" : "=v"(r) : "v"(lo), "v"(hi)); return r; }
;     DI void operator()(const f32x4 (&acc)[2][2][4][2], const Unit& u, int wr, int wc, int fr, int fq) const {
;     ...
;             if (rope) {
; #pragma unroll
;                 for (int m = 0; m < 4; ++m) { const int pos = (rowb + ai * HALF + m * 16) & (SEQ - 1); c4[m] = *(const f32x4*)(cs + pos * 64 + fi); s4[m] = *(const f32x4*)(sn + pos * 64 + fi); }
;             }
;             asm volatile("" ::: "memory");
; #pragma unroll
;             for (int m = 0; m < 4; ++m) {
;                 const int row = rowb + ai * HALF + m * 16;
;                 float t = (sl[ai][m][0] + sl[ai][m][1]) + (sl[ai][m][2] + sl[ai][m][3]);
;                 t += __shfl_xor(t, 16); t += __shfl_xor(t, 32);
;                 const float rs = __builtin_amdgcn_rsqf(t * (1.0f / D) + EPS);
; #pragma unroll
;                 for (int bj = 0; bj < 2; ++bj) {
;                     f32x4 v0 = acc[ai][bj][m][0] * rs, v1 = acc[ai][bj][m][1] * rs;
;                     if (rope) { const f32x4 o0 = (v0 * c4[m] - v1 * s4[m]) * ksc, o1 = (v0 * s4[m] + v1 * c4[m]) * ksc; v0 = o0; v1 = o1; }
;                     u32x4 w; w.x = pk2(v0[0], v0[1]); w.y = pk2(v0[2], v0[3]); w.z = pk2(v1[0], v1[1]); w.w = pk2(v1[2], v1[3]);
;                     *(u32x4*)(Z + (size_t)row * INW + col0 + bj * HALF) = w;
;                 }
	v_pk_mul_f32 v[30:31], v[30:31], v[240:241] op_sel_hi:[1,0]
	v_pk_mul_f32 v[32:33], v[32:33], v[240:241] op_sel_hi:[1,0]
	v_pk_mul_f32 v[26:27], v[26:27], v[240:241] op_sel_hi:[1,0]
	v_pk_mul_f32 v[28:29], v[28:29], v[240:241] op_sel_hi:[1,0]
	v_pk_mul_f32 v[200:201], v[182:183], v[26:27]
	v_pk_mul_f32 v[236:237], v[178:179], v[26:27]
	v_pk_mul_f32 v[202:203], v[184:185], v[28:29]
	v_pk_mul_f32 v[238:239], v[180:181], v[28:29]
	v_pk_fma_f32 v[26:27], v[182:183], v[30:31], v[236:237]
	v_pk_fma_f32 v[30:31], v[178:179], v[30:31], v[200:201] neg_lo:[0,0,1] neg_hi:[0,0,1]
	v_pk_fma_f32 v[28:29], v[184:185], v[32:33], v[238:239]
	v_pk_fma_f32 v[32:33], v[180:181], v[32:33], v[202:203] neg_lo:[0,0,1] neg_hi:[0,0,1]
	v_pk_mul_f32 v[30:31], v[30:31], v[224:225] op_sel_hi:[1,0]
	v_pk_mul_f32 v[32:33], v[32:33], v[224:225] op_sel_hi:[1,0]
	v_pk_mul_f32 v[26:27], v[26:27], v[224:225] op_sel_hi:[1,0]
	v_pk_mul_f32 v[28:29], v[28:29], v[224:225] op_sel_hi:[1,0]
	v_cvt_pk_bf16_f32 v66, v30, v31
	v_cvt_pk_bf16_f32 v67, v32, v33
	v_cvt_pk_bf16_f32 v68, v26, v27
	v_cvt_pk_bf16_f32 v69, v28, v29
	v_pk_mul_f32 v[22:23], v[22:23], v[240:241] op_sel_hi:[1,0]
	v_pk_mul_f32 v[24:25], v[24:25], v[240:241] op_sel_hi:[1,0]
	v_pk_mul_f32 v[18:19], v[18:19], v[240:241] op_sel_hi:[1,0]
	v_pk_mul_f32 v[20:21], v[20:21], v[240:241] op_sel_hi:[1,0]
	v_pk_mul_f32 v[200:201], v[182:183], v[18:19]
	v_pk_mul_f32 v[236:237], v[178:179], v[18:19]
	v_pk_mul_f32 v[202:203], v[184:185], v[20:21]
	v_pk_mul_f32 v[238:239], v[180:181], v[20:21]
	v_pk_fma_f32 v[18:19], v[182:183], v[22:23], v[236:237]
	v_pk_fma_f32 v[22:23], v[178:179], v[22:23], v[200:201] neg_lo:[0,0,1] neg_hi:[0,0,1]
	v_pk_fma_f32 v[20:21], v[184:185], v[24:25], v[238:239]
	v_pk_fma_f32 v[24:25], v[180:181], v[24:25], v[202:203] neg_lo:[0,0,1] neg_hi:[0,0,1]
	v_pk_mul_f32 v[22:23], v[22:23], v[224:225] op_sel_hi:[1,0]
	v_pk_mul_f32 v[24:25], v[24:25], v[224:225] op_sel_hi:[1,0]
	v_pk_mul_f32 v[18:19], v[18:19], v[224:225] op_sel_hi:[1,0]
	v_pk_mul_f32 v[20:21], v[20:21], v[224:225] op_sel_hi:[1,0]
	v_cvt_pk_bf16_f32 v78, v22, v23
	v_cvt_pk_bf16_f32 v79, v24, v25
	v_cvt_pk_bf16_f32 v80, v18, v19
	v_cvt_pk_bf16_f32 v81, v20, v21
	global_store_dwordx4 v144, v[66:69], s[48:49]
	global_store_dwordx4 v144, v[78:81], s[48:49] offset:256
	s_waitcnt vmcnt(8)
	v_pk_mul_f32 v[14:15], v[14:15], v[240:241] op_sel:[0,1] op_sel_hi:[1,1]
	v_pk_mul_f32 v[16:17], v[16:17], v[240:241] op_sel:[0,1] op_sel_hi:[1,1]
	v_pk_mul_f32 v[10:11], v[10:11], v[240:241] op_sel:[0,1] op_sel_hi:[1,1]
	v_pk_mul_f32 v[12:13], v[12:13], v[240:241] op_sel:[0,1] op_sel_hi:[1,1]
	v_pk_mul_f32 v[200:201], v[190:191], v[10:11]
	v_pk_mul_f32 v[236:237], v[186:187], v[10:11]
	v_pk_mul_f32 v[202:203], v[192:193], v[12:13]
	v_pk_mul_f32 v[238:239], v[188:189], v[12:13]
	v_pk_fma_f32 v[10:11], v[190:191], v[14:15], v[236:237]
	v_pk_fma_f32 v[14:15], v[186:187], v[14:15], v[200:201] neg_lo:[0,0,1] neg_hi:[0,0,1]
	v_pk_fma_f32 v[12:13], v[192:193], v[16:17], v[238:239]
	v_pk_fma_f32 v[16:17], v[188:189], v[16:17], v[202:203] neg_lo:[0,0,1] neg_hi:[0,0,1]
	v_pk_mul_f32 v[14:15], v[14:15], v[224:225] op_sel_hi:[1,0]
	v_pk_mul_f32 v[16:17], v[16:17], v[224:225] op_sel_hi:[1,0]
	v_pk_mul_f32 v[10:11], v[10:11], v[224:225] op_sel_hi:[1,0]
	v_pk_mul_f32 v[12:13], v[12:13], v[224:225] op_sel_hi:[1,0]
	v_cvt_pk_bf16_f32 v66, v14, v15
	v_cvt_pk_bf16_f32 v67, v16, v17
	v_cvt_pk_bf16_f32 v68, v10, v11
	v_cvt_pk_bf16_f32 v69, v12, v13
	v_pk_mul_f32 v[6:7], v[6:7], v[240:241] op_sel:[0,1] op_sel_hi:[1,1]
	v_pk_mul_f32 v[8:9], v[8:9], v[240:241] op_sel:[0,1] op_sel_hi:[1,1]
	v_pk_mul_f32 v[2:3], v[2:3], v[240:241] op_sel:[0,1] op_sel_hi:[1,1]
	v_pk_mul_f32 v[4:5], v[4:5], v[240:241] op_sel:[0,1] op_sel_hi:[1,1]
	v_pk_mul_f32 v[200:201], v[190:191], v[2:3]
	v_pk_mul_f32 v[236:237], v[186:187], v[2:3]
	v_pk_mul_f32 v[202:203], v[192:193], v[4:5]
	v_pk_mul_f32 v[238:239], v[188:189], v[4:5]
	v_pk_fma_f32 v[2:3], v[190:191], v[6:7], v[236:237]
	v_pk_fma_f32 v[6:7], v[186:187], v[6:7], v[200:201] neg_lo:[0,0,1] neg_hi:[0,0,1]
	v_pk_fma_f32 v[4:5], v[192:193], v[8:9], v[238:239]
	v_pk_fma_f32 v[8:9], v[188:189], v[8:9], v[202:203] neg_lo:[0,0,1] neg_hi:[0,0,1]
	v_pk_mul_f32 v[6:7], v[6:7], v[224:225] op_sel_hi:[1,0]
	v_pk_mul_f32 v[8:9], v[8:9], v[224:225] op_sel_hi:[1,0]
	v_pk_mul_f32 v[2:3], v[2:3], v[224:225] op_sel_hi:[1,0]
	v_pk_mul_f32 v[4:5], v[4:5], v[224:225] op_sel_hi:[1,0]
	v_cvt_pk_bf16_f32 v78, v6, v7
	v_cvt_pk_bf16_f32 v79, v8, v9
	v_cvt_pk_bf16_f32 v80, v2, v3
	v_cvt_pk_bf16_f32 v81, v4, v5
	global_store_dwordx4 v145, v[66:69], s[48:49]
	global_store_dwordx4 v145, v[78:81], s[48:49] offset:256
	s_branch .Lwin_epi_done
